# sample-path Toeplitz stream with 16x16x32 MFMAs (4 per block product) + accumulator layout permutation at the end
# baseline (speedup 1.0000x reference)
.LBB0_456:
	s_or_b64 exec, exec, s[48:49]
	s_waitcnt vmcnt(1)
	v_lshlrev_b32_e32 v6, 16, v10
	v_and_b32_e32 v10, 0xffff0000, v10
	v_mov_b32_e32 v22, v10
	v_and_b32_e32 v47, 16, v12
	v_and_b32_e32 v46, 0xffff0000, v11
	v_lshlrev_b32_e32 v11, 16, v11
	s_waitcnt vmcnt(1)
	v_lshlrev_b32_e32 v23, 16, v23
	v_pk_mul_f32 v[22:23], v[30:31], v[22:23]
	v_mov_b32_e32 v24, v31
	v_mov_b32_e32 v25, v31
	v_mov_b32_e32 v32, v30
	v_mov_b32_e32 v33, v30
	s_waitcnt vmcnt(0)
	v_lshlrev_b32_e32 v7, 16, v7
	v_pk_fma_f32 v[22:23], v[30:31], v[6:7], v[22:23] op_sel:[0,0,1] op_sel_hi:[1,0,0]
	v_pk_mov_b32 v[30:31], v[10:11], v[46:47] op_sel:[1,0]
	v_mov_b32_e32 v29, v28
	v_and_b32_e32 v39, 0xffff0000, v13
	v_and_b32_e32 v41, 16, v13
	v_and_b32_e32 v40, 0xffff0000, v12
	v_lshlrev_b32_e32 v45, 16, v13
	v_lshlrev_b32_e32 v13, 16, v12
	v_mov_b32_e32 v12, v46
	v_pk_mul_f32 v[30:31], v[32:33], v[30:31]
	v_pk_fma_f32 v[22:23], v[28:29], v[10:11], v[22:23]
	v_pk_fma_f32 v[10:11], v[24:25], v[10:11], v[30:31]
	v_pk_mov_b32 v[30:31], v[12:13], v[40:41] op_sel:[1,0]
	v_mov_b32_e32 v38, v45
	v_pk_mul_f32 v[30:31], v[32:33], v[30:31]
	v_mov_b32_e32 v44, v40
	v_pk_fma_f32 v[10:11], v[28:29], v[12:13], v[10:11]
	v_pk_fma_f32 v[12:13], v[24:25], v[12:13], v[30:31]
	v_pk_mul_f32 v[30:31], v[32:33], v[38:39]
	v_mov_b32_e32 v8, v39
	v_pk_fma_f32 v[24:25], v[24:25], v[44:45], v[30:31]
	s_waitcnt vmcnt(0)
	v_lshlrev_b32_e32 v31, 16, v5
	v_mov_b32_e32 v36, v18
	v_mov_b32_e32 v37, v18
	v_pk_fma_f32 v[12:13], v[28:29], v[44:45], v[12:13]
	s_waitcnt vmcnt(1)
	v_lshlrev_b32_e32 v9, 16, v9
	v_pk_fma_f32 v[8:9], v[28:29], v[8:9], v[24:25]
	v_and_b32_e32 v25, 0xffff0000, v5
	v_and_b32_e32 v28, 0xffff0000, v4
	v_mov_b32_e32 v24, v31
	v_mov_b32_e32 v34, v19
	v_mov_b32_e32 v35, v19
	v_mov_b32_e32 v30, v28
	v_pk_mul_f32 v[32:33], v[36:37], v[24:25]
	v_mov_b32_e32 v17, v16
	v_pk_fma_f32 v[32:33], v[34:35], v[30:31], v[32:33]
	v_mov_b32_e32 v20, v25
	s_waitcnt vmcnt(0)
	v_lshlrev_b32_e32 v21, 16, v21
	v_pk_fma_f32 v[20:21], v[16:17], v[20:21], v[32:33]
	v_and_b32_e32 v32, 0xffff0000, v2
	v_mov_b32_e32 v27, v26
	v_and_b32_e32 v25, 16, v4
	v_and_b32_e32 v24, 0xffff0000, v3
	v_lshlrev_b32_e32 v33, 16, v3
	v_mov_b32_e32 v6, v32
	v_pk_add_f32 v[22:23], v[26:27], v[22:23]
	v_pk_add_f32 v[10:11], v[26:27], v[10:11]
	v_pk_add_f32 v[12:13], v[26:27], v[12:13]
	v_pk_add_f32 v[8:9], v[26:27], v[8:9]
	v_lshlrev_b32_e32 v26, 16, v2
	v_pk_mul_f32 v[2:3], v[18:19], v[6:7]
	v_pk_mov_b32 v[6:7], v[32:33], v[24:25] op_sel:[1,0]
	v_and_b32_e32 v29, 16, v5
	v_pk_mul_f32 v[6:7], v[36:37], v[6:7]
	v_lshlrev_b32_e32 v5, 16, v4
	v_mov_b32_e32 v4, v24
	v_pk_fma_f32 v[2:3], v[18:19], v[26:27], v[2:3] op_sel:[0,0,1] op_sel_hi:[1,0,0]
	v_pk_fma_f32 v[6:7], v[34:35], v[32:33], v[6:7]
	v_mov_b32_e32 v15, v14
	v_pk_fma_f32 v[2:3], v[16:17], v[32:33], v[2:3]
	v_pk_fma_f32 v[6:7], v[16:17], v[4:5], v[6:7]
	v_pk_add_f32 v[2:3], v[14:15], v[2:3]
	v_pk_add_f32 v[6:7], v[14:15], v[6:7]
	v_pk_mul_f32 v[2:3], v[22:23], v[2:3]
	v_pk_mul_f32 v[6:7], v[10:11], v[6:7]
	v_cvt_pk_bf16_f32 v2, v2, v3
	v_cvt_pk_bf16_f32 v3, v6, v7
	v_pk_mov_b32 v[6:7], v[4:5], v[28:29] op_sel:[1,0]
	v_pk_add_f32 v[20:21], v[14:15], v[20:21]
	v_pk_mul_f32 v[6:7], v[36:37], v[6:7]
	s_mov_b64 s[48:49], -1
	v_pk_fma_f32 v[4:5], v[34:35], v[4:5], v[6:7]
	v_pk_mul_f32 v[6:7], v[8:9], v[20:21]
	v_pk_fma_f32 v[4:5], v[16:17], v[30:31], v[4:5]
	s_nop 0
	v_pk_add_f32 v[4:5], v[14:15], v[4:5]
	s_nop 0
	v_pk_mul_f32 v[4:5], v[12:13], v[4:5]
	s_nop 0
	v_cvt_pk_bf16_f32 v4, v4, v5
	v_cvt_pk_bf16_f32 v5, v6, v7
	v_add_u32_e32 v6, s44, v43
	s_and_b64 s[44:45], s[30:31], exec
	v_add_u32_e32 v183, v6, v42
	s_cselect_b32 s44, 10, 14
	ds_write_b128 v183, v[2:5]
	v_lshlrev_b32_e32 v2, s44, v163
	v_add_u32_e32 v117, 0, v2
	v_mov_b32_e32 v2, s47
	v_mad_u32_u24 v182, s85, v163, v2
	v_sub_u32_e32 v2, s46, v111
	v_add_u32_e32 v184, v2, v120
	v_lshrrev_b32_e32 v2, s93, v164
	v_mul_u32_u24_e32 v2, s91, v2
	v_and_b32_e32 v3, s92, v111
	v_add3_u32 v180, v2, s90, v3
	v_lshlrev_b32_e32 v2, 1, v184
	v_add_u32_e32 v3, 0x7f, v180
	s_andn2_b64 vcc, exec, s[42:43]
	v_and_b32_e32 v185, 2, v2
	v_lshrrev_b32_e32 v187, 2, v3
	v_lshlrev_b32_e32 v186, 6, v3
	s_waitcnt lgkmcnt(0)
	s_barrier
	s_cbranch_vccnz .LBB0_472
	v_mov_b32_e32 v2, 0
	v_mov_b32_e32 v3, v2
	v_mov_b32_e32 v4, v2
	v_mov_b32_e32 v5, v2
	v_mov_b32_e32 v6, v2
	v_mov_b32_e32 v7, v2
	v_mov_b32_e32 v8, v2
	v_mov_b32_e32 v9, v2
	v_mov_b32_e32 v10, v2
	v_mov_b32_e32 v11, v2
	v_mov_b32_e32 v12, v2
	v_mov_b32_e32 v13, v2
	v_mov_b32_e32 v14, v2
	v_mov_b32_e32 v15, v2
	v_mov_b32_e32 v16, v2
	v_mov_b32_e32 v17, v2
	v_mov_b32_e32 v18, v2
	v_mov_b32_e32 v19, v2
	v_mov_b32_e32 v20, v2
	v_mov_b32_e32 v21, v2
	v_mov_b32_e32 v22, v2
	v_mov_b32_e32 v23, v2
	v_mov_b32_e32 v24, v2
	v_mov_b32_e32 v25, v2
	v_mov_b32_e32 v26, v2
	v_mov_b32_e32 v27, v2
	v_mov_b32_e32 v28, v2
	v_mov_b32_e32 v29, v2
	v_mov_b32_e32 v30, v2
	v_mov_b32_e32 v31, v2
	v_mov_b32_e32 v32, v2
	v_mov_b32_e32 v33, v2
	v_mov_b32_e32 v34, v2
	v_mov_b32_e32 v35, v2
	v_mov_b32_e32 v36, v2
	v_mov_b32_e32 v37, v2
	v_mov_b32_e32 v38, v2
	v_mov_b32_e32 v39, v2
	v_mov_b32_e32 v40, v2
	v_mov_b32_e32 v41, v2
	v_mov_b32_e32 v42, v2
	v_mov_b32_e32 v43, v2
	v_mov_b32_e32 v44, v2
	v_mov_b32_e32 v45, v2
	v_mov_b32_e32 v46, v2
	v_mov_b32_e32 v47, v2
	v_mov_b32_e32 v48, v2
	v_mov_b32_e32 v49, v2
	v_mov_b32_e32 v50, v2
	v_mov_b32_e32 v51, v2
	v_mov_b32_e32 v52, v2
	v_mov_b32_e32 v53, v2
	v_mov_b32_e32 v54, v2
	v_mov_b32_e32 v55, v2
	v_mov_b32_e32 v56, v2
	v_mov_b32_e32 v57, v2
	v_mov_b32_e32 v58, v2
	v_mov_b32_e32 v59, v2
	v_mov_b32_e32 v60, v2
	v_mov_b32_e32 v61, v2
	v_mov_b32_e32 v62, v2
	v_mov_b32_e32 v63, v2
	v_mov_b32_e32 v64, v2
	v_mov_b32_e32 v65, v2
	v_and_b32_e32 v210, 15, v1
	v_bfe_u32 v188, v1, 4, 2
	v_and_b32_e32 v208, 1, v210
	v_lshlrev_b32_e32 v208, 1, v208
	v_lshlrev_b32_e32 v206, 3, v188
	v_add_u32_e32 v206, 0x1000, v206
	v_sub_u32_e32 v206, v206, v210
	v_lshlrev_b32_e32 v206, 1, v206
	v_and_b32_e32 v206, -4, v206
	v_add_u32_e32 v206, 0x1fa0, v206
	v_add_u32_e32 v206, v117, v206
	v_bfe_u32 v209, v1, 6, 1
	v_mul_u32_u24_e32 v209, 0x9f, v209
	v_add_u32_e32 v209, v209, v210
	v_add_u32_e32 v209, 0x9e, v209
	v_lshrrev_b32_e32 v210, 2, v209
	v_lshl_add_u32 v189, v209, 6, v182
	v_bitop3_b32 v211, v210, v188, 3 bitop3:0x6c
	v_lshl_add_u32 v207, v211, 4, v189
	ds_read2_b32 v[194:195], v206 offset1:1
	ds_read2_b32 v[196:197], v206 offset0:2 offset1:3
	ds_read_b32 v198, v206 offset:16
	ds_read2_b32 v[200:201], v206 offset0:8 offset1:9
	ds_read2_b32 v[202:203], v206 offset0:10 offset1:11
	ds_read_b32 v204, v206 offset:48
	ds_read_b128 v[66:69], v207
	ds_read_b128 v[70:73], v207 offset:1024
	v_add_u32_e32 v209, -1, v209
	v_lshrrev_b32_e32 v210, 2, v209
	v_lshl_add_u32 v189, v209, 6, v182
	v_bitop3_b32 v211, v210, v188, 3 bitop3:0x6c
	v_lshl_add_u32 v207, v211, 4, v189
	s_movk_i32 s42, 0xff81
.Ltoep_seg0:
	s_waitcnt lgkmcnt(2)
	v_alignbyte_b32 v98, v195, v194, v208
	v_alignbyte_b32 v99, v196, v195, v208
	v_alignbyte_b32 v100, v197, v196, v208
	v_alignbyte_b32 v101, v198, v197, v208
	v_alignbyte_b32 v102, v201, v200, v208
	v_alignbyte_b32 v103, v202, v201, v208
	v_alignbyte_b32 v104, v203, v202, v208
	v_alignbyte_b32 v105, v204, v203, v208
	v_add_u32_e32 v206, -64, v206
	ds_read2_b32 v[194:195], v206 offset1:1
	ds_read2_b32 v[196:197], v206 offset0:2 offset1:3
	ds_read_b32 v198, v206 offset:16
	ds_read2_b32 v[200:201], v206 offset0:8 offset1:9
	ds_read2_b32 v[202:203], v206 offset0:10 offset1:11
	ds_read_b32 v204, v206 offset:48
	s_waitcnt lgkmcnt(7)
	v_mfma_f32_16x16x32_bf16 v[2:5], v[102:105], v[66:69], v[2:5]
	v_mfma_f32_16x16x32_bf16 v[10:13], v[98:101], v[66:69], v[10:13]
	ds_read_b128 v[66:69], v207
	v_add_u32_e32 v209, -1, v209
	v_lshrrev_b32_e32 v210, 2, v209
	s_waitcnt lgkmcnt(7)
	v_mfma_f32_16x16x32_bf16 v[6:9], v[102:105], v[70:73], v[6:9]
	v_mfma_f32_16x16x32_bf16 v[14:17], v[98:101], v[70:73], v[14:17]
	ds_read_b128 v[70:73], v207 offset:1024
	v_lshl_add_u32 v189, v209, 6, v182
	v_bitop3_b32 v211, v210, v188, 3 bitop3:0x6c
	v_lshl_add_u32 v207, v211, 4, v189
	s_addk_i32 s42, 0x1
	s_cmpk_lt_i32 s42, 0xffa1
	s_cbranch_scc1 .Ltoep_seg0
	v_add_u32_e32 v210, 1, v209
	v_lshl_add_u32 v189, v210, 6, v182
	v_lshrrev_b32_e32 v210, 2, v210
	v_bitop3_b32 v211, v210, v188, 3 bitop3:0x6c
	v_lshl_add_u32 v199, v211, 4, v189
	ds_read_b128 v[74:77], v199 offset:2048
	ds_read_b128 v[78:81], v199 offset:3072
	s_waitcnt lgkmcnt(0)
.Ltoep_seg1:
	s_waitcnt lgkmcnt(4)
	v_alignbyte_b32 v98, v195, v194, v208
	v_alignbyte_b32 v99, v196, v195, v208
	v_alignbyte_b32 v100, v197, v196, v208
	v_alignbyte_b32 v101, v198, v197, v208
	v_alignbyte_b32 v102, v201, v200, v208
	v_alignbyte_b32 v103, v202, v201, v208
	v_alignbyte_b32 v104, v203, v202, v208
	v_alignbyte_b32 v105, v204, v203, v208
	v_add_u32_e32 v206, -64, v206
	ds_read2_b32 v[194:195], v206 offset1:1
	ds_read2_b32 v[196:197], v206 offset0:2 offset1:3
	ds_read_b32 v198, v206 offset:16
	ds_read2_b32 v[200:201], v206 offset0:8 offset1:9
	ds_read2_b32 v[202:203], v206 offset0:10 offset1:11
	ds_read_b32 v204, v206 offset:48
	s_waitcnt lgkmcnt(9)
	v_mfma_f32_16x16x32_bf16 v[2:5], v[102:105], v[66:69], v[2:5]
	v_mfma_f32_16x16x32_bf16 v[10:13], v[98:101], v[66:69], v[10:13]
	ds_read_b128 v[66:69], v207
	v_add_u32_e32 v209, -1, v209
	s_waitcnt lgkmcnt(9)
	v_mfma_f32_16x16x32_bf16 v[6:9], v[102:105], v[70:73], v[6:9]
	v_mfma_f32_16x16x32_bf16 v[14:17], v[98:101], v[70:73], v[14:17]
	ds_read_b128 v[70:73], v207 offset:1024
	v_lshrrev_b32_e32 v210, 2, v209
	s_waitcnt lgkmcnt(9)
	v_mfma_f32_16x16x32_bf16 v[18:21], v[102:105], v[74:77], v[18:21]
	v_mfma_f32_16x16x32_bf16 v[26:29], v[98:101], v[74:77], v[26:29]
	ds_read_b128 v[74:77], v207 offset:2048
	v_lshl_add_u32 v189, v209, 6, v182
	s_waitcnt lgkmcnt(9)
	v_mfma_f32_16x16x32_bf16 v[22:25], v[102:105], v[78:81], v[22:25]
	v_mfma_f32_16x16x32_bf16 v[30:33], v[98:101], v[78:81], v[30:33]
	ds_read_b128 v[78:81], v207 offset:3072
	v_bitop3_b32 v211, v210, v188, 3 bitop3:0x6c
	v_lshl_add_u32 v207, v211, 4, v189
	s_addk_i32 s42, 0x1
	s_cmpk_lt_i32 s42, 0xffc1
	s_cbranch_scc1 .Ltoep_seg1
	v_add_u32_e32 v210, 1, v209
	v_lshl_add_u32 v189, v210, 6, v182
	v_lshrrev_b32_e32 v210, 2, v210
	v_bitop3_b32 v211, v210, v188, 3 bitop3:0x6c
	v_lshl_add_u32 v199, v211, 4, v189
	ds_read_b128 v[82:85], v199 offset:4096
	ds_read_b128 v[86:89], v199 offset:5120
	s_waitcnt lgkmcnt(0)
.Ltoep_seg2:
	s_waitcnt lgkmcnt(6)
	v_alignbyte_b32 v98, v195, v194, v208
	v_alignbyte_b32 v99, v196, v195, v208
	v_alignbyte_b32 v100, v197, v196, v208
	v_alignbyte_b32 v101, v198, v197, v208
	v_alignbyte_b32 v102, v201, v200, v208
	v_alignbyte_b32 v103, v202, v201, v208
	v_alignbyte_b32 v104, v203, v202, v208
	v_alignbyte_b32 v105, v204, v203, v208
	v_add_u32_e32 v206, -64, v206
	ds_read2_b32 v[194:195], v206 offset1:1
	ds_read2_b32 v[196:197], v206 offset0:2 offset1:3
	ds_read_b32 v198, v206 offset:16
	ds_read2_b32 v[200:201], v206 offset0:8 offset1:9
	ds_read2_b32 v[202:203], v206 offset0:10 offset1:11
	ds_read_b32 v204, v206 offset:48
	s_waitcnt lgkmcnt(11)
	v_mfma_f32_16x16x32_bf16 v[2:5], v[102:105], v[66:69], v[2:5]
	v_mfma_f32_16x16x32_bf16 v[10:13], v[98:101], v[66:69], v[10:13]
	ds_read_b128 v[66:69], v207
	v_add_u32_e32 v209, -1, v209
	s_waitcnt lgkmcnt(11)
	v_mfma_f32_16x16x32_bf16 v[6:9], v[102:105], v[70:73], v[6:9]
	v_mfma_f32_16x16x32_bf16 v[14:17], v[98:101], v[70:73], v[14:17]
	ds_read_b128 v[70:73], v207 offset:1024
	v_lshrrev_b32_e32 v210, 2, v209
	s_waitcnt lgkmcnt(11)
	v_mfma_f32_16x16x32_bf16 v[18:21], v[102:105], v[74:77], v[18:21]
	v_mfma_f32_16x16x32_bf16 v[26:29], v[98:101], v[74:77], v[26:29]
	ds_read_b128 v[74:77], v207 offset:2048
	s_waitcnt lgkmcnt(11)
	v_mfma_f32_16x16x32_bf16 v[22:25], v[102:105], v[78:81], v[22:25]
	v_mfma_f32_16x16x32_bf16 v[30:33], v[98:101], v[78:81], v[30:33]
	ds_read_b128 v[78:81], v207 offset:3072
	v_lshl_add_u32 v189, v209, 6, v182
	s_waitcnt lgkmcnt(11)
	v_mfma_f32_16x16x32_bf16 v[34:37], v[102:105], v[82:85], v[34:37]
	v_mfma_f32_16x16x32_bf16 v[42:45], v[98:101], v[82:85], v[42:45]
	ds_read_b128 v[82:85], v207 offset:4096
	v_bitop3_b32 v211, v210, v188, 3 bitop3:0x6c
	s_waitcnt lgkmcnt(11)
	v_mfma_f32_16x16x32_bf16 v[38:41], v[102:105], v[86:89], v[38:41]
	v_mfma_f32_16x16x32_bf16 v[46:49], v[98:101], v[86:89], v[46:49]
	ds_read_b128 v[86:89], v207 offset:5120
	v_lshl_add_u32 v207, v211, 4, v189
	s_addk_i32 s42, 0x1
	s_cmpk_lt_i32 s42, 0xffe1
	s_cbranch_scc1 .Ltoep_seg2
	v_add_u32_e32 v210, 1, v209
	v_lshl_add_u32 v189, v210, 6, v182
	v_lshrrev_b32_e32 v210, 2, v210
	v_bitop3_b32 v211, v210, v188, 3 bitop3:0x6c
	v_lshl_add_u32 v199, v211, 4, v189
	ds_read_b128 v[90:93], v199 offset:6144
	ds_read_b128 v[94:97], v199 offset:7168
	s_waitcnt lgkmcnt(0)
.Ltoep_seg3:
	s_waitcnt lgkmcnt(8)
	v_alignbyte_b32 v98, v195, v194, v208
	v_alignbyte_b32 v99, v196, v195, v208
	v_alignbyte_b32 v100, v197, v196, v208
	v_alignbyte_b32 v101, v198, v197, v208
	v_alignbyte_b32 v102, v201, v200, v208
	v_alignbyte_b32 v103, v202, v201, v208
	v_alignbyte_b32 v104, v203, v202, v208
	v_alignbyte_b32 v105, v204, v203, v208
	v_add_u32_e32 v206, -64, v206
	ds_read2_b32 v[194:195], v206 offset1:1
	ds_read2_b32 v[196:197], v206 offset0:2 offset1:3
	ds_read_b32 v198, v206 offset:16
	ds_read2_b32 v[200:201], v206 offset0:8 offset1:9
	ds_read2_b32 v[202:203], v206 offset0:10 offset1:11
	ds_read_b32 v204, v206 offset:48
	s_waitcnt lgkmcnt(13)
	v_mfma_f32_16x16x32_bf16 v[2:5], v[102:105], v[66:69], v[2:5]
	v_mfma_f32_16x16x32_bf16 v[10:13], v[98:101], v[66:69], v[10:13]
	ds_read_b128 v[66:69], v207
	v_add_u32_e32 v209, -1, v209
	s_waitcnt lgkmcnt(13)
	v_mfma_f32_16x16x32_bf16 v[6:9], v[102:105], v[70:73], v[6:9]
	v_mfma_f32_16x16x32_bf16 v[14:17], v[98:101], v[70:73], v[14:17]
	ds_read_b128 v[70:73], v207 offset:1024
	s_waitcnt lgkmcnt(13)
	v_mfma_f32_16x16x32_bf16 v[18:21], v[102:105], v[74:77], v[18:21]
	v_mfma_f32_16x16x32_bf16 v[26:29], v[98:101], v[74:77], v[26:29]
	ds_read_b128 v[74:77], v207 offset:2048
	v_lshrrev_b32_e32 v210, 2, v209
	s_waitcnt lgkmcnt(13)
	v_mfma_f32_16x16x32_bf16 v[22:25], v[102:105], v[78:81], v[22:25]
	v_mfma_f32_16x16x32_bf16 v[30:33], v[98:101], v[78:81], v[30:33]
	ds_read_b128 v[78:81], v207 offset:3072
	s_waitcnt lgkmcnt(13)
	v_mfma_f32_16x16x32_bf16 v[34:37], v[102:105], v[82:85], v[34:37]
	v_mfma_f32_16x16x32_bf16 v[42:45], v[98:101], v[82:85], v[42:45]
	ds_read_b128 v[82:85], v207 offset:4096
	v_lshl_add_u32 v189, v209, 6, v182
	s_waitcnt lgkmcnt(13)
	v_mfma_f32_16x16x32_bf16 v[38:41], v[102:105], v[86:89], v[38:41]
	v_mfma_f32_16x16x32_bf16 v[46:49], v[98:101], v[86:89], v[46:49]
	ds_read_b128 v[86:89], v207 offset:5120
	s_waitcnt lgkmcnt(13)
	v_mfma_f32_16x16x32_bf16 v[50:53], v[102:105], v[90:93], v[50:53]
	v_mfma_f32_16x16x32_bf16 v[58:61], v[98:101], v[90:93], v[58:61]
	ds_read_b128 v[90:93], v207 offset:6144
	v_bitop3_b32 v211, v210, v188, 3 bitop3:0x6c
	s_waitcnt lgkmcnt(13)
	v_mfma_f32_16x16x32_bf16 v[54:57], v[102:105], v[94:97], v[54:57]
	v_mfma_f32_16x16x32_bf16 v[62:65], v[98:101], v[94:97], v[62:65]
	ds_read_b128 v[94:97], v207 offset:7168
	v_lshl_add_u32 v207, v211, 4, v189
	s_addk_i32 s42, 0x1
	s_cmpk_lt_i32 s42, 0x20
	s_cbranch_scc1 .Ltoep_seg3
	s_waitcnt lgkmcnt(0)
.Ltoep_seg4:
	s_waitcnt lgkmcnt(6)
	v_alignbyte_b32 v98, v195, v194, v208
	v_alignbyte_b32 v99, v196, v195, v208
	v_alignbyte_b32 v100, v197, v196, v208
	v_alignbyte_b32 v101, v198, v197, v208
	v_alignbyte_b32 v102, v201, v200, v208
	v_alignbyte_b32 v103, v202, v201, v208
	v_alignbyte_b32 v104, v203, v202, v208
	v_alignbyte_b32 v105, v204, v203, v208
	v_add_u32_e32 v206, -64, v206
	ds_read2_b32 v[194:195], v206 offset1:1
	ds_read2_b32 v[196:197], v206 offset0:2 offset1:3
	ds_read_b32 v198, v206 offset:16
	ds_read2_b32 v[200:201], v206 offset0:8 offset1:9
	ds_read2_b32 v[202:203], v206 offset0:10 offset1:11
	ds_read_b32 v204, v206 offset:48
	s_waitcnt lgkmcnt(11)
	v_mfma_f32_16x16x32_bf16 v[18:21], v[102:105], v[74:77], v[18:21]
	v_mfma_f32_16x16x32_bf16 v[26:29], v[98:101], v[74:77], v[26:29]
	ds_read_b128 v[74:77], v207 offset:2048
	v_add_u32_e32 v209, -1, v209
	s_waitcnt lgkmcnt(11)
	v_mfma_f32_16x16x32_bf16 v[22:25], v[102:105], v[78:81], v[22:25]
	v_mfma_f32_16x16x32_bf16 v[30:33], v[98:101], v[78:81], v[30:33]
	ds_read_b128 v[78:81], v207 offset:3072
	v_lshrrev_b32_e32 v210, 2, v209
	s_waitcnt lgkmcnt(11)
	v_mfma_f32_16x16x32_bf16 v[34:37], v[102:105], v[82:85], v[34:37]
	v_mfma_f32_16x16x32_bf16 v[42:45], v[98:101], v[82:85], v[42:45]
	ds_read_b128 v[82:85], v207 offset:4096
	s_waitcnt lgkmcnt(11)
	v_mfma_f32_16x16x32_bf16 v[38:41], v[102:105], v[86:89], v[38:41]
	v_mfma_f32_16x16x32_bf16 v[46:49], v[98:101], v[86:89], v[46:49]
	ds_read_b128 v[86:89], v207 offset:5120
	v_lshl_add_u32 v189, v209, 6, v182
	s_waitcnt lgkmcnt(11)
	v_mfma_f32_16x16x32_bf16 v[50:53], v[102:105], v[90:93], v[50:53]
	v_mfma_f32_16x16x32_bf16 v[58:61], v[98:101], v[90:93], v[58:61]
	ds_read_b128 v[90:93], v207 offset:6144
	v_bitop3_b32 v211, v210, v188, 3 bitop3:0x6c
	s_waitcnt lgkmcnt(11)
	v_mfma_f32_16x16x32_bf16 v[54:57], v[102:105], v[94:97], v[54:57]
	v_mfma_f32_16x16x32_bf16 v[62:65], v[98:101], v[94:97], v[62:65]
	ds_read_b128 v[94:97], v207 offset:7168
	v_lshl_add_u32 v207, v211, 4, v189
	s_addk_i32 s42, 0x1
	s_cmpk_lt_i32 s42, 0x40
	s_cbranch_scc1 .Ltoep_seg4
	s_waitcnt lgkmcnt(0)
.Ltoep_seg5:
	s_waitcnt lgkmcnt(4)
	v_alignbyte_b32 v98, v195, v194, v208
	v_alignbyte_b32 v99, v196, v195, v208
	v_alignbyte_b32 v100, v197, v196, v208
	v_alignbyte_b32 v101, v198, v197, v208
	v_alignbyte_b32 v102, v201, v200, v208
	v_alignbyte_b32 v103, v202, v201, v208
	v_alignbyte_b32 v104, v203, v202, v208
	v_alignbyte_b32 v105, v204, v203, v208
	v_add_u32_e32 v206, -64, v206
	ds_read2_b32 v[194:195], v206 offset1:1
	ds_read2_b32 v[196:197], v206 offset0:2 offset1:3
	ds_read_b32 v198, v206 offset:16
	ds_read2_b32 v[200:201], v206 offset0:8 offset1:9
	ds_read2_b32 v[202:203], v206 offset0:10 offset1:11
	ds_read_b32 v204, v206 offset:48
	s_waitcnt lgkmcnt(9)
	v_mfma_f32_16x16x32_bf16 v[34:37], v[102:105], v[82:85], v[34:37]
	v_mfma_f32_16x16x32_bf16 v[42:45], v[98:101], v[82:85], v[42:45]
	ds_read_b128 v[82:85], v207 offset:4096
	v_add_u32_e32 v209, -1, v209
	s_waitcnt lgkmcnt(9)
	v_mfma_f32_16x16x32_bf16 v[38:41], v[102:105], v[86:89], v[38:41]
	v_mfma_f32_16x16x32_bf16 v[46:49], v[98:101], v[86:89], v[46:49]
	ds_read_b128 v[86:89], v207 offset:5120
	v_lshrrev_b32_e32 v210, 2, v209
	s_waitcnt lgkmcnt(9)
	v_mfma_f32_16x16x32_bf16 v[50:53], v[102:105], v[90:93], v[50:53]
	v_mfma_f32_16x16x32_bf16 v[58:61], v[98:101], v[90:93], v[58:61]
	ds_read_b128 v[90:93], v207 offset:6144
	v_lshl_add_u32 v189, v209, 6, v182
	s_waitcnt lgkmcnt(9)
	v_mfma_f32_16x16x32_bf16 v[54:57], v[102:105], v[94:97], v[54:57]
	v_mfma_f32_16x16x32_bf16 v[62:65], v[98:101], v[94:97], v[62:65]
	ds_read_b128 v[94:97], v207 offset:7168
	v_bitop3_b32 v211, v210, v188, 3 bitop3:0x6c
	v_lshl_add_u32 v207, v211, 4, v189
	s_addk_i32 s42, 0x1
	s_cmpk_lt_i32 s42, 0x60
	s_cbranch_scc1 .Ltoep_seg5
	s_waitcnt lgkmcnt(0)
.Ltoep_seg6:
	s_waitcnt lgkmcnt(2)
	v_alignbyte_b32 v98, v195, v194, v208
	v_alignbyte_b32 v99, v196, v195, v208
	v_alignbyte_b32 v100, v197, v196, v208
	v_alignbyte_b32 v101, v198, v197, v208
	v_alignbyte_b32 v102, v201, v200, v208
	v_alignbyte_b32 v103, v202, v201, v208
	v_alignbyte_b32 v104, v203, v202, v208
	v_alignbyte_b32 v105, v204, v203, v208
	v_add_u32_e32 v206, -64, v206
	ds_read2_b32 v[194:195], v206 offset1:1
	ds_read2_b32 v[196:197], v206 offset0:2 offset1:3
	ds_read_b32 v198, v206 offset:16
	ds_read2_b32 v[200:201], v206 offset0:8 offset1:9
	ds_read2_b32 v[202:203], v206 offset0:10 offset1:11
	ds_read_b32 v204, v206 offset:48
	s_waitcnt lgkmcnt(7)
	v_mfma_f32_16x16x32_bf16 v[50:53], v[102:105], v[90:93], v[50:53]
	v_mfma_f32_16x16x32_bf16 v[58:61], v[98:101], v[90:93], v[58:61]
	ds_read_b128 v[90:93], v207 offset:6144
	v_add_u32_e32 v209, -1, v209
	v_lshrrev_b32_e32 v210, 2, v209
	s_waitcnt lgkmcnt(7)
	v_mfma_f32_16x16x32_bf16 v[54:57], v[102:105], v[94:97], v[54:57]
	v_mfma_f32_16x16x32_bf16 v[62:65], v[98:101], v[94:97], v[62:65]
	ds_read_b128 v[94:97], v207 offset:7168
	v_lshl_add_u32 v189, v209, 6, v182
	v_bitop3_b32 v211, v210, v188, 3 bitop3:0x6c
	v_lshl_add_u32 v207, v211, 4, v189
	s_addk_i32 s42, 0x1
	s_cmpk_lt_i32 s42, 0x7f
	s_cbranch_scc1 .Ltoep_seg6
	s_waitcnt lgkmcnt(0)
	v_alignbyte_b32 v98, v195, v194, v208
	v_alignbyte_b32 v99, v196, v195, v208
	v_alignbyte_b32 v100, v197, v196, v208
	v_alignbyte_b32 v101, v198, v197, v208
	v_alignbyte_b32 v102, v201, v200, v208
	v_alignbyte_b32 v103, v202, v201, v208
	v_alignbyte_b32 v104, v203, v202, v208
	v_alignbyte_b32 v105, v204, v203, v208
	s_nop 1
	v_mfma_f32_16x16x32_bf16 v[50:53], v[102:105], v[90:93], v[50:53]
	v_mfma_f32_16x16x32_bf16 v[54:57], v[102:105], v[94:97], v[54:57]
	v_mfma_f32_16x16x32_bf16 v[58:61], v[98:101], v[90:93], v[58:61]
	v_mfma_f32_16x16x32_bf16 v[62:65], v[98:101], v[94:97], v[62:65]
	s_nop 15
	v_bfe_u32 v210, v1, 5, 1
	v_and_b32_e32 v211, 15, v1
	v_lshlrev_b32_e32 v210, 6, v210
	v_lshl_add_u32 v209, v211, 2, v210
	v_add_u32_e32 v199, 0x80, v209
	v_bfe_u32 v210, v1, 4, 1
	v_cmp_ne_u32_e32 vcc, 0, v210
	ds_bpermute_b32 v82, v209, v2
	ds_bpermute_b32 v83, v209, v6
	ds_bpermute_b32 v84, v209, v3
	ds_bpermute_b32 v85, v209, v7
	ds_bpermute_b32 v86, v209, v4
	ds_bpermute_b32 v87, v209, v8
	ds_bpermute_b32 v88, v209, v5
	ds_bpermute_b32 v89, v209, v9
	ds_bpermute_b32 v90, v199, v2
	ds_bpermute_b32 v91, v199, v6
	ds_bpermute_b32 v92, v199, v3
	ds_bpermute_b32 v93, v199, v7
	ds_bpermute_b32 v94, v199, v4
	ds_bpermute_b32 v95, v199, v8
	ds_bpermute_b32 v96, v199, v5
	ds_bpermute_b32 v97, v199, v9
	s_waitcnt lgkmcnt(0)
	v_cndmask_b32_e32 v66, v82, v83, vcc
	v_cndmask_b32_e32 v67, v84, v85, vcc
	v_cndmask_b32_e32 v68, v86, v87, vcc
	v_cndmask_b32_e32 v69, v88, v89, vcc
	v_cndmask_b32_e32 v70, v90, v91, vcc
	v_cndmask_b32_e32 v71, v92, v93, vcc
	v_cndmask_b32_e32 v72, v94, v95, vcc
	v_cndmask_b32_e32 v73, v96, v97, vcc
	ds_bpermute_b32 v82, v209, v10
	ds_bpermute_b32 v83, v209, v14
	ds_bpermute_b32 v84, v209, v11
	ds_bpermute_b32 v85, v209, v15
	ds_bpermute_b32 v86, v209, v12
	ds_bpermute_b32 v87, v209, v16
	ds_bpermute_b32 v88, v209, v13
	ds_bpermute_b32 v89, v209, v17
	ds_bpermute_b32 v90, v199, v10
	ds_bpermute_b32 v91, v199, v14
	ds_bpermute_b32 v92, v199, v11
	ds_bpermute_b32 v93, v199, v15
	ds_bpermute_b32 v94, v199, v12
	ds_bpermute_b32 v95, v199, v16
	ds_bpermute_b32 v96, v199, v13
	ds_bpermute_b32 v97, v199, v17
	s_waitcnt lgkmcnt(0)
	v_cndmask_b32_e32 v74, v82, v83, vcc
	v_cndmask_b32_e32 v75, v84, v85, vcc
	v_cndmask_b32_e32 v76, v86, v87, vcc
	v_cndmask_b32_e32 v77, v88, v89, vcc
	v_cndmask_b32_e32 v78, v90, v91, vcc
	v_cndmask_b32_e32 v79, v92, v93, vcc
	v_cndmask_b32_e32 v80, v94, v95, vcc
	v_cndmask_b32_e32 v81, v96, v97, vcc
	v_mov_b32_e32 v2, v66
	v_mov_b32_e32 v3, v67
	v_mov_b32_e32 v4, v68
	v_mov_b32_e32 v5, v69
	v_mov_b32_e32 v6, v70
	v_mov_b32_e32 v7, v71
	v_mov_b32_e32 v8, v72
	v_mov_b32_e32 v9, v73
	v_mov_b32_e32 v10, v74
	v_mov_b32_e32 v11, v75
	v_mov_b32_e32 v12, v76
	v_mov_b32_e32 v13, v77
	v_mov_b32_e32 v14, v78
	v_mov_b32_e32 v15, v79
	v_mov_b32_e32 v16, v80
	v_mov_b32_e32 v17, v81
	ds_bpermute_b32 v82, v209, v18
	ds_bpermute_b32 v83, v209, v22
	ds_bpermute_b32 v84, v209, v19
	ds_bpermute_b32 v85, v209, v23
	ds_bpermute_b32 v86, v209, v20
	ds_bpermute_b32 v87, v209, v24
	ds_bpermute_b32 v88, v209, v21
	ds_bpermute_b32 v89, v209, v25
	ds_bpermute_b32 v90, v199, v18
	ds_bpermute_b32 v91, v199, v22
	ds_bpermute_b32 v92, v199, v19
	ds_bpermute_b32 v93, v199, v23
	ds_bpermute_b32 v94, v199, v20
	ds_bpermute_b32 v95, v199, v24
	ds_bpermute_b32 v96, v199, v21
	ds_bpermute_b32 v97, v199, v25
	s_waitcnt lgkmcnt(0)
	v_cndmask_b32_e32 v66, v82, v83, vcc
	v_cndmask_b32_e32 v67, v84, v85, vcc
	v_cndmask_b32_e32 v68, v86, v87, vcc
	v_cndmask_b32_e32 v69, v88, v89, vcc
	v_cndmask_b32_e32 v70, v90, v91, vcc
	v_cndmask_b32_e32 v71, v92, v93, vcc
	v_cndmask_b32_e32 v72, v94, v95, vcc
	v_cndmask_b32_e32 v73, v96, v97, vcc
	ds_bpermute_b32 v82, v209, v26
	ds_bpermute_b32 v83, v209, v30
	ds_bpermute_b32 v84, v209, v27
	ds_bpermute_b32 v85, v209, v31
	ds_bpermute_b32 v86, v209, v28
	ds_bpermute_b32 v87, v209, v32
	ds_bpermute_b32 v88, v209, v29
	ds_bpermute_b32 v89, v209, v33
	ds_bpermute_b32 v90, v199, v26
	ds_bpermute_b32 v91, v199, v30
	ds_bpermute_b32 v92, v199, v27
	ds_bpermute_b32 v93, v199, v31
	ds_bpermute_b32 v94, v199, v28
	ds_bpermute_b32 v95, v199, v32
	ds_bpermute_b32 v96, v199, v29
	ds_bpermute_b32 v97, v199, v33
	s_waitcnt lgkmcnt(0)
	v_cndmask_b32_e32 v74, v82, v83, vcc
	v_cndmask_b32_e32 v75, v84, v85, vcc
	v_cndmask_b32_e32 v76, v86, v87, vcc
	v_cndmask_b32_e32 v77, v88, v89, vcc
	v_cndmask_b32_e32 v78, v90, v91, vcc
	v_cndmask_b32_e32 v79, v92, v93, vcc
	v_cndmask_b32_e32 v80, v94, v95, vcc
	v_cndmask_b32_e32 v81, v96, v97, vcc
	v_mov_b32_e32 v18, v66
	v_mov_b32_e32 v19, v67
	v_mov_b32_e32 v20, v68
	v_mov_b32_e32 v21, v69
	v_mov_b32_e32 v22, v70
	v_mov_b32_e32 v23, v71
	v_mov_b32_e32 v24, v72
	v_mov_b32_e32 v25, v73
	v_mov_b32_e32 v26, v74
	v_mov_b32_e32 v27, v75
	v_mov_b32_e32 v28, v76
	v_mov_b32_e32 v29, v77
	v_mov_b32_e32 v30, v78
	v_mov_b32_e32 v31, v79
	v_mov_b32_e32 v32, v80
	v_mov_b32_e32 v33, v81
	ds_bpermute_b32 v82, v209, v34
	ds_bpermute_b32 v83, v209, v38
	ds_bpermute_b32 v84, v209, v35
	ds_bpermute_b32 v85, v209, v39
	ds_bpermute_b32 v86, v209, v36
	ds_bpermute_b32 v87, v209, v40
	ds_bpermute_b32 v88, v209, v37
	ds_bpermute_b32 v89, v209, v41
	ds_bpermute_b32 v90, v199, v34
	ds_bpermute_b32 v91, v199, v38
	ds_bpermute_b32 v92, v199, v35
	ds_bpermute_b32 v93, v199, v39
	ds_bpermute_b32 v94, v199, v36
	ds_bpermute_b32 v95, v199, v40
	ds_bpermute_b32 v96, v199, v37
	ds_bpermute_b32 v97, v199, v41
	s_waitcnt lgkmcnt(0)
	v_cndmask_b32_e32 v66, v82, v83, vcc
	v_cndmask_b32_e32 v67, v84, v85, vcc
	v_cndmask_b32_e32 v68, v86, v87, vcc
	v_cndmask_b32_e32 v69, v88, v89, vcc
	v_cndmask_b32_e32 v70, v90, v91, vcc
	v_cndmask_b32_e32 v71, v92, v93, vcc
	v_cndmask_b32_e32 v72, v94, v95, vcc
	v_cndmask_b32_e32 v73, v96, v97, vcc
	ds_bpermute_b32 v82, v209, v42
	ds_bpermute_b32 v83, v209, v46
	ds_bpermute_b32 v84, v209, v43
	ds_bpermute_b32 v85, v209, v47
	ds_bpermute_b32 v86, v209, v44
	ds_bpermute_b32 v87, v209, v48
	ds_bpermute_b32 v88, v209, v45
	ds_bpermute_b32 v89, v209, v49
	ds_bpermute_b32 v90, v199, v42
	ds_bpermute_b32 v91, v199, v46
	ds_bpermute_b32 v92, v199, v43
	ds_bpermute_b32 v93, v199, v47
	ds_bpermute_b32 v94, v199, v44
	ds_bpermute_b32 v95, v199, v48
	ds_bpermute_b32 v96, v199, v45
	ds_bpermute_b32 v97, v199, v49
	s_waitcnt lgkmcnt(0)
	v_cndmask_b32_e32 v74, v82, v83, vcc
	v_cndmask_b32_e32 v75, v84, v85, vcc
	v_cndmask_b32_e32 v76, v86, v87, vcc
	v_cndmask_b32_e32 v77, v88, v89, vcc
	v_cndmask_b32_e32 v78, v90, v91, vcc
	v_cndmask_b32_e32 v79, v92, v93, vcc
	v_cndmask_b32_e32 v80, v94, v95, vcc
	v_cndmask_b32_e32 v81, v96, v97, vcc
	v_mov_b32_e32 v34, v66
	v_mov_b32_e32 v35, v67
	v_mov_b32_e32 v36, v68
	v_mov_b32_e32 v37, v69
	v_mov_b32_e32 v38, v70
	v_mov_b32_e32 v39, v71
	v_mov_b32_e32 v40, v72
	v_mov_b32_e32 v41, v73
	v_mov_b32_e32 v42, v74
	v_mov_b32_e32 v43, v75
	v_mov_b32_e32 v44, v76
	v_mov_b32_e32 v45, v77
	v_mov_b32_e32 v46, v78
	v_mov_b32_e32 v47, v79
	v_mov_b32_e32 v48, v80
	v_mov_b32_e32 v49, v81
	ds_bpermute_b32 v82, v209, v50
	ds_bpermute_b32 v83, v209, v54
	ds_bpermute_b32 v84, v209, v51
	ds_bpermute_b32 v85, v209, v55
	ds_bpermute_b32 v86, v209, v52
	ds_bpermute_b32 v87, v209, v56
	ds_bpermute_b32 v88, v209, v53
	ds_bpermute_b32 v89, v209, v57
	ds_bpermute_b32 v90, v199, v50
	ds_bpermute_b32 v91, v199, v54
	ds_bpermute_b32 v92, v199, v51
	ds_bpermute_b32 v93, v199, v55
	ds_bpermute_b32 v94, v199, v52
	ds_bpermute_b32 v95, v199, v56
	ds_bpermute_b32 v96, v199, v53
	ds_bpermute_b32 v97, v199, v57
	s_waitcnt lgkmcnt(0)
	v_cndmask_b32_e32 v66, v82, v83, vcc
	v_cndmask_b32_e32 v67, v84, v85, vcc
	v_cndmask_b32_e32 v68, v86, v87, vcc
	v_cndmask_b32_e32 v69, v88, v89, vcc
	v_cndmask_b32_e32 v70, v90, v91, vcc
	v_cndmask_b32_e32 v71, v92, v93, vcc
	v_cndmask_b32_e32 v72, v94, v95, vcc
	v_cndmask_b32_e32 v73, v96, v97, vcc
	ds_bpermute_b32 v82, v209, v58
	ds_bpermute_b32 v83, v209, v62
	ds_bpermute_b32 v84, v209, v59
	ds_bpermute_b32 v85, v209, v63
	ds_bpermute_b32 v86, v209, v60
	ds_bpermute_b32 v87, v209, v64
	ds_bpermute_b32 v88, v209, v61
	ds_bpermute_b32 v89, v209, v65
	ds_bpermute_b32 v90, v199, v58
	ds_bpermute_b32 v91, v199, v62
	ds_bpermute_b32 v92, v199, v59
	ds_bpermute_b32 v93, v199, v63
	ds_bpermute_b32 v94, v199, v60
	ds_bpermute_b32 v95, v199, v64
	ds_bpermute_b32 v96, v199, v61
	ds_bpermute_b32 v97, v199, v65
	s_waitcnt lgkmcnt(0)
	v_cndmask_b32_e32 v74, v82, v83, vcc
	v_cndmask_b32_e32 v75, v84, v85, vcc
	v_cndmask_b32_e32 v76, v86, v87, vcc
	v_cndmask_b32_e32 v77, v88, v89, vcc
	v_cndmask_b32_e32 v78, v90, v91, vcc
	v_cndmask_b32_e32 v79, v92, v93, vcc
	v_cndmask_b32_e32 v80, v94, v95, vcc
	v_cndmask_b32_e32 v81, v96, v97, vcc
	v_mov_b32_e32 v50, v66
	v_mov_b32_e32 v51, v67
	v_mov_b32_e32 v52, v68
	v_mov_b32_e32 v53, v69
	v_mov_b32_e32 v54, v70
	v_mov_b32_e32 v55, v71
	v_mov_b32_e32 v56, v72
	v_mov_b32_e32 v57, v73
	v_mov_b32_e32 v58, v74
	v_mov_b32_e32 v59, v75
	v_mov_b32_e32 v60, v76
	v_mov_b32_e32 v61, v77
	v_mov_b32_e32 v62, v78
	v_mov_b32_e32 v63, v79
	v_mov_b32_e32 v64, v80
	v_mov_b32_e32 v65, v81
	s_mov_b64 s[48:49], 0
